# filter_mlp weight prefetch only (without the pointer-fetch change), for comparison with the later variants
# speedup vs baseline: 1.0021x; 1.0021x over previous
; __device__ void filter_mlp_phase(unsigned char* smem, int l) {
;     ...
;     for (int tile = blockIdx.x; tile < 256; tile += gridDim.x) {
;         const int pos = tile * 8 + ps;
;         __syncthreads();
;         if (u < 33) { float f;
;             if (u == 0) f = (float)pos / 2047.0f;
;             else { const int bi = (u - 1) & 15; const float fb = 1e-4f + (float)bi * ((15.0f - 1e-4f) / 15.0f); const float wpos = 6.283185307179586f * (float)pos / 2048.0f; const float arg = fb * wpos;
;                 f = (u <= 16) ? sin_acc(arg, 1.5707963267948966) : -sin_acc(arg, 0.0); }
;             zz[ps * 36 + u] = f; }
;         __syncthreads();
;         { float a = b1[u];
; #pragma unroll 3
;             for (int k = 0; k < 33; ++k) a += zz[ps * 36 + k] * w1[k * 64 + u]; ha[ps * 64 + u] = sin_acc(fr[u] * a, 0.0); }
;         __syncthreads();
;         { float a = b2[u];
; #pragma unroll 4
;             for (int k = 0; k < 64; ++k) a += ha[ps * 64 + k] * w2[k * 64 + u]; hb[ps * 64 + u] = sin_acc(fr[u] * a, 0.0); }
.LBB0_383:
	s_mov_b32 s100, 0x1200
	s_mov_b32 s101, 0
	global_load_dword v230, v[0:1], off
	global_load_dword v231, v[4:5], off
	global_load_dword v232, v[6:7], off
	global_load_dword v233, v[2:3], off
	global_load_dword v48, v[8:9], off offset:-512
	global_load_dword v49, v[8:9], off offset:-256
	global_load_dword v50, v[8:9], off
	global_load_dword v51, v[8:9], off offset:256
	global_load_dword v52, v[8:9], off offset:512
	global_load_dword v53, v[8:9], off offset:768
	global_load_dword v54, v[8:9], off offset:1024
	global_load_dword v55, v[8:9], off offset:1280
	global_load_dword v56, v[8:9], off offset:1536
	global_load_dword v57, v[8:9], off offset:1792
	global_load_dword v58, v[8:9], off offset:2048
	global_load_dword v59, v[8:9], off offset:2304
	global_load_dword v60, v[8:9], off offset:2560
	global_load_dword v61, v[8:9], off offset:2816
	global_load_dword v62, v[8:9], off offset:3072
	global_load_dword v63, v[8:9], off offset:3328
	global_load_dword v64, v[8:9], off offset:3584
	global_load_dword v65, v[8:9], off offset:3840
	v_lshl_add_u64 v[14:15], v[8:9], 0, s[100:101]
	global_load_dword v66, v[14:15], off offset:-512
	global_load_dword v67, v[14:15], off offset:-256
	global_load_dword v68, v[14:15], off
	global_load_dword v69, v[14:15], off offset:256
	global_load_dword v70, v[14:15], off offset:512
	global_load_dword v71, v[14:15], off offset:768
	global_load_dword v72, v[14:15], off offset:1024
	global_load_dword v73, v[14:15], off offset:1280
	global_load_dword v74, v[14:15], off offset:1536
	global_load_dword v75, v[14:15], off offset:1792
	global_load_dword v76, v[14:15], off offset:2048
	global_load_dword v77, v[14:15], off offset:2304
	global_load_dword v78, v[14:15], off offset:2560
	global_load_dword v79, v[14:15], off offset:2816
	global_load_dword v80, v[14:15], off offset:3072
	global_load_dword v81, v[10:11], off offset:-512
	global_load_dword v82, v[10:11], off offset:-256
	global_load_dword v83, v[10:11], off
	global_load_dword v84, v[10:11], off offset:256
	global_load_dword v85, v[10:11], off offset:512
	global_load_dword v86, v[10:11], off offset:768
	global_load_dword v87, v[10:11], off offset:1024
	global_load_dword v88, v[10:11], off offset:1280
	global_load_dword v89, v[10:11], off offset:1536
	global_load_dword v90, v[10:11], off offset:1792
	global_load_dword v91, v[10:11], off offset:2048
	global_load_dword v92, v[10:11], off offset:2304
	global_load_dword v93, v[10:11], off offset:2560
	global_load_dword v94, v[10:11], off offset:2816
	global_load_dword v95, v[10:11], off offset:3072
	global_load_dword v96, v[10:11], off offset:3328
	global_load_dword v97, v[10:11], off offset:3584
	global_load_dword v98, v[10:11], off offset:3840
	v_lshl_add_u64 v[14:15], v[10:11], 0, s[100:101]
	global_load_dword v99, v[14:15], off offset:-512
	global_load_dword v100, v[14:15], off offset:-256
	global_load_dword v101, v[14:15], off
	global_load_dword v102, v[14:15], off offset:256
	global_load_dword v103, v[14:15], off offset:512
	global_load_dword v104, v[14:15], off offset:768
	global_load_dword v105, v[14:15], off offset:1024
	global_load_dword v106, v[14:15], off offset:1280
	global_load_dword v107, v[14:15], off offset:1536
	global_load_dword v108, v[14:15], off offset:1792
	global_load_dword v109, v[14:15], off offset:2048
	global_load_dword v110, v[14:15], off offset:2304
	global_load_dword v111, v[14:15], off offset:2560
	global_load_dword v112, v[14:15], off offset:2816
	global_load_dword v113, v[14:15], off offset:3072
	global_load_dword v114, v[14:15], off offset:3328
	global_load_dword v115, v[14:15], off offset:3584
	global_load_dword v116, v[14:15], off offset:3840
	v_lshl_add_u64 v[14:15], v[14:15], 0, s[100:101]
	global_load_dword v117, v[14:15], off offset:-512
	global_load_dword v118, v[14:15], off offset:-256
	global_load_dword v119, v[14:15], off
	global_load_dword v120, v[14:15], off offset:256
	global_load_dword v121, v[14:15], off offset:512
	global_load_dword v122, v[14:15], off offset:768
	global_load_dword v123, v[14:15], off offset:1024
	global_load_dword v124, v[14:15], off offset:1280
	global_load_dword v125, v[14:15], off offset:1536
	global_load_dword v126, v[14:15], off offset:1792
	global_load_dword v127, v[14:15], off offset:2048
	global_load_dword v128, v[14:15], off offset:2304
	global_load_dword v129, v[14:15], off offset:2560
	global_load_dword v130, v[14:15], off offset:2816
	global_load_dword v131, v[14:15], off offset:3072
	global_load_dword v132, v[14:15], off offset:3328
	global_load_dword v133, v[14:15], off offset:3584
	global_load_dword v134, v[14:15], off offset:3840
	v_lshl_add_u64 v[14:15], v[14:15], 0, s[100:101]
	global_load_dword v135, v[14:15], off offset:-512
	global_load_dword v136, v[14:15], off offset:-256
	global_load_dword v137, v[14:15], off
	global_load_dword v138, v[14:15], off offset:256
	global_load_dword v139, v[14:15], off offset:512
	global_load_dword v142, v[14:15], off offset:768
	global_load_dword v143, v[14:15], off offset:1024
	global_load_dword v144, v[14:15], off offset:1280
	global_load_dword v145, v[14:15], off offset:1536
	global_load_dword v146, v[14:15], off offset:1792
	v_lshl_add_u32 v24, s14, 3, v17
	s_barrier
	s_and_saveexec_b64 s[12:13], s[0:1]
	s_cbranch_execz .LBB0_393
	v_cvt_f32_i32_e32 v14, v24
	s_and_saveexec_b64 s[16:17], s[8:9]
	s_xor_b64 s[16:17], exec, s[16:17]
	s_cbranch_execz .LBB0_390
	v_mul_f32_e32 v14, 0x40c90fdb, v14
	v_mul_f32_e32 v14, 0x3a000000, v14
	v_mul_f32_e32 v14, v18, v14
	v_cvt_f64_f32_e32 v[14:15], v14
	s_and_saveexec_b64 s[18:19], s[10:11]
	s_xor_b64 s[18:19], exec, s[18:19]
	s_cbranch_execz .LBB0_387
	v_add_f64 v[14:15], v[14:15], 0
	v_mul_f64 v[26:27], v[14:15], s[22:23]
	v_rndne_f64_e32 v[26:27], v[26:27]
	v_fmac_f64_e32 v[14:15], s[28:29], v[26:27]
	v_mul_f64 v[26:27], v[14:15], v[14:15]
	v_mov_b64_e32 v[28:29], v[188:189]
	v_fmac_f64_e32 v[28:29], s[30:31], v[26:27]
	v_mov_b64_e32 v[30:31], v[190:191]
	v_fmac_f64_e32 v[30:31], v[26:27], v[28:29]
	v_mov_b64_e32 v[28:29], v[192:193]
	v_fmac_f64_e32 v[28:29], v[26:27], v[30:31]
	v_mov_b64_e32 v[30:31], v[194:195]
	v_fmac_f64_e32 v[30:31], v[26:27], v[28:29]
	v_mov_b64_e32 v[28:29], v[196:197]
	v_fmac_f64_e32 v[28:29], v[26:27], v[30:31]
	v_mov_b64_e32 v[30:31], v[198:199]
	v_fmac_f64_e32 v[30:31], v[26:27], v[28:29]
	v_mov_b64_e32 v[28:29], v[200:201]
	v_fmac_f64_e32 v[28:29], v[26:27], v[30:31]
	v_mov_b64_e32 v[30:31], v[202:203]
	v_fmac_f64_e32 v[30:31], v[26:27], v[28:29]
	v_mov_b64_e32 v[28:29], v[204:205]
	v_fmac_f64_e32 v[28:29], v[26:27], v[30:31]
	v_mul_f64 v[26:27], v[14:15], v[26:27]
	v_fma_f64 v[14:15], -v[26:27], v[28:29], v[14:15]
	v_cvt_f32_f64_e64 v25, -v[14:15]

; __device__ void filter_mlp_phase(unsigned char* smem, int l) {
;     ...
;         { float a = b1[u];
; #pragma unroll 3
;             for (int k = 0; k < 33; ++k) a += zz[ps * 36 + k] * w1[k * 64 + u]; ha[ps * 64 + u] = sin_acc(fr[u] * a, 0.0); }
;         __syncthreads();
;         { float a = b2[u];
; #pragma unroll 4
;             for (int k = 0; k < 64; ++k) a += ha[ps * 64 + k] * w2[k * 64 + u]; hb[ps * 64 + u] = sin_acc(fr[u] * a, 0.0); }
;         __syncthreads();
;         { float a = b3[u];
; #pragma unroll 4
;             for (int k = 0; k < 64; ++k) a += hb[ps * 64 + k] * w3[k * 64 + u]; hdn[pos * 64 + u] = sin_acc(fr[u] * a, 0.0); }
.LBB0_393:
	s_or_b64 exec, exec, s[12:13]
	s_waitcnt lgkmcnt(0)
	s_barrier
	s_waitcnt vmcnt(0)
	v_mov_b32_e32 v25, v230
	ds_read_b128 v[26:29], v19
	ds_read_b128 v[30:33], v19 offset:16
	s_waitcnt lgkmcnt(1)
	v_fmac_f32_e32 v25, v26, v48
	v_fmac_f32_e32 v25, v27, v49
	v_fmac_f32_e32 v25, v28, v50
	v_fmac_f32_e32 v25, v29, v51
	s_waitcnt lgkmcnt(0)
	v_fmac_f32_e32 v25, v30, v52
	v_fmac_f32_e32 v25, v31, v53
	v_fmac_f32_e32 v25, v32, v54
	v_fmac_f32_e32 v25, v33, v55
	ds_read_b128 v[26:29], v19 offset:32
	ds_read_b128 v[30:33], v19 offset:48
	s_waitcnt lgkmcnt(1)
	v_fmac_f32_e32 v25, v26, v56
	v_fmac_f32_e32 v25, v27, v57
	v_fmac_f32_e32 v25, v28, v58
	v_fmac_f32_e32 v25, v29, v59
	s_waitcnt lgkmcnt(0)
	v_fmac_f32_e32 v25, v30, v60
	v_fmac_f32_e32 v25, v31, v61
	v_fmac_f32_e32 v25, v32, v62
	v_fmac_f32_e32 v25, v33, v63
	ds_read_b128 v[26:29], v19 offset:64
	ds_read_b128 v[30:33], v19 offset:80
	s_waitcnt lgkmcnt(1)
	v_fmac_f32_e32 v25, v26, v64
	v_fmac_f32_e32 v25, v27, v65
	v_fmac_f32_e32 v25, v28, v66
	v_fmac_f32_e32 v25, v29, v67
	s_waitcnt lgkmcnt(0)
	v_fmac_f32_e32 v25, v30, v68
	v_fmac_f32_e32 v25, v31, v69
	v_fmac_f32_e32 v25, v32, v70
	v_fmac_f32_e32 v25, v33, v71
	ds_read_b128 v[26:29], v19 offset:96
	ds_read_b128 v[30:33], v19 offset:112
	s_waitcnt lgkmcnt(1)
	v_fmac_f32_e32 v25, v26, v72
	v_fmac_f32_e32 v25, v27, v73
	v_fmac_f32_e32 v25, v28, v74
	v_fmac_f32_e32 v25, v29, v75
	s_waitcnt lgkmcnt(0)
	v_fmac_f32_e32 v25, v30, v76
	v_fmac_f32_e32 v25, v31, v77
	v_fmac_f32_e32 v25, v32, v78
	v_fmac_f32_e32 v25, v33, v79
	ds_read_b32 v26, v19 offset:128
	s_waitcnt lgkmcnt(0)
	v_fmac_f32_e32 v25, v26, v80
	global_load_dword v48, v[12:13], off offset:-512
	global_load_dword v49, v[12:13], off offset:-256
	global_load_dword v50, v[12:13], off
	global_load_dword v51, v[12:13], off offset:256
	global_load_dword v52, v[12:13], off offset:512
	global_load_dword v53, v[12:13], off offset:768
	global_load_dword v54, v[12:13], off offset:1024
	global_load_dword v55, v[12:13], off offset:1280
	global_load_dword v56, v[12:13], off offset:1536
	global_load_dword v57, v[12:13], off offset:1792
	global_load_dword v58, v[12:13], off offset:2048
	global_load_dword v59, v[12:13], off offset:2304
	global_load_dword v60, v[12:13], off offset:2560
	global_load_dword v61, v[12:13], off offset:2816
	global_load_dword v62, v[12:13], off offset:3072
	global_load_dword v63, v[12:13], off offset:3328
	global_load_dword v64, v[12:13], off offset:3584
	global_load_dword v65, v[12:13], off offset:3840
	v_lshl_add_u64 v[14:15], v[12:13], 0, s[100:101]
	global_load_dword v66, v[14:15], off offset:-512
	global_load_dword v67, v[14:15], off offset:-256
	global_load_dword v68, v[14:15], off
	global_load_dword v69, v[14:15], off offset:256
	global_load_dword v70, v[14:15], off offset:512
	global_load_dword v71, v[14:15], off offset:768
	global_load_dword v72, v[14:15], off offset:1024
	global_load_dword v73, v[14:15], off offset:1280
	global_load_dword v74, v[14:15], off offset:1536
	global_load_dword v75, v[14:15], off offset:1792
	global_load_dword v76, v[14:15], off offset:2048
	global_load_dword v77, v[14:15], off offset:2304
	global_load_dword v78, v[14:15], off offset:2560
	global_load_dword v79, v[14:15], off offset:2816
	global_load_dword v80, v[14:15], off offset:3072
	global_load_dword v147, v[14:15], off offset:3328
	global_load_dword v148, v[14:15], off offset:3584
	global_load_dword v149, v[14:15], off offset:3840
	v_lshl_add_u64 v[14:15], v[14:15], 0, s[100:101]
	global_load_dword v150, v[14:15], off offset:-512
	global_load_dword v151, v[14:15], off offset:-256
	global_load_dword v152, v[14:15], off
	global_load_dword v153, v[14:15], off offset:256
	global_load_dword v154, v[14:15], off offset:512
	global_load_dword v155, v[14:15], off offset:768
	global_load_dword v156, v[14:15], off offset:1024
	global_load_dword v157, v[14:15], off offset:1280
	global_load_dword v158, v[14:15], off offset:1536
	global_load_dword v159, v[14:15], off offset:1792
	global_load_dword v160, v[14:15], off offset:2048
	global_load_dword v161, v[14:15], off offset:2304
	global_load_dword v162, v[14:15], off offset:2560
	global_load_dword v163, v[14:15], off offset:2816
	global_load_dword v164, v[14:15], off offset:3072
	global_load_dword v165, v[14:15], off offset:3328
	global_load_dword v166, v[14:15], off offset:3584
	global_load_dword v167, v[14:15], off offset:3840
	v_lshl_add_u64 v[14:15], v[14:15], 0, s[100:101]
	global_load_dword v168, v[14:15], off offset:-512
	global_load_dword v169, v[14:15], off offset:-256
	global_load_dword v170, v[14:15], off
	global_load_dword v171, v[14:15], off offset:256
	global_load_dword v172, v[14:15], off offset:512
	global_load_dword v173, v[14:15], off offset:768
	global_load_dword v174, v[14:15], off offset:1024
	global_load_dword v175, v[14:15], off offset:1280
	global_load_dword v176, v[14:15], off offset:1536
	global_load_dword v177, v[14:15], off offset:1792
	v_mov_b32_e32 v42, v233
	v_mov_b64_e32 v[14:15], v[188:189]
	v_mov_b64_e32 v[26:27], v[190:191]
	v_mov_b64_e32 v[28:29], v[192:193]
	v_mov_b64_e32 v[30:31], v[194:195]
	v_mov_b64_e32 v[32:33], v[196:197]
	v_mov_b64_e32 v[34:35], v[198:199]
	v_mov_b64_e32 v[36:37], v[200:201]
	v_mov_b64_e32 v[38:39], v[202:203]
	v_mov_b64_e32 v[40:41], v[204:205]
	s_mov_b32 s12, 0
	v_mul_f32_e32 v25, v25, v42
	v_cvt_f64_f32_e32 v[42:43], v25
	v_add_f64 v[42:43], v[42:43], 0
	v_mul_f64 v[44:45], v[42:43], s[22:23]
	v_rndne_f64_e32 v[44:45], v[44:45]
	v_fmac_f64_e32 v[42:43], s[28:29], v[44:45]
	v_mul_f64 v[44:45], v[42:43], v[42:43]
	v_fmac_f64_e32 v[14:15], s[30:31], v[44:45]
	v_fmac_f64_e32 v[26:27], v[44:45], v[14:15]
	v_fmac_f64_e32 v[28:29], v[44:45], v[26:27]
	v_fmac_f64_e32 v[30:31], v[44:45], v[28:29]
	v_fmac_f64_e32 v[32:33], v[44:45], v[30:31]
	v_fmac_f64_e32 v[34:35], v[44:45], v[32:33]
	v_fmac_f64_e32 v[36:37], v[44:45], v[34:35]
	v_fmac_f64_e32 v[38:39], v[44:45], v[36:37]
	v_mul_f64 v[46:47], v[42:43], v[44:45]
	v_fmac_f64_e32 v[40:41], v[44:45], v[38:39]
	v_fma_f64 v[14:15], -v[46:47], v[40:41], v[42:43]
	v_cvt_f32_f64_e32 v14, v[14:15]
	ds_write_b32 v20, v14 offset:1152
	s_waitcnt lgkmcnt(0)
	s_barrier
; __device__ __forceinline__ float sin_acc(float x, double shift) {
;     double xd = (double)x + shift; const double k = rint(xd * 0.15915494309189535); double r = xd - k * 6.283185307179586;
;     const double r2 = r * r; double s = -1.0 / 51090942171709440000.0;
;     s = s * r2 + 1.0 / 121645100408832000.0; s = s * r2 - 1.0 / 355687428096000.0; s = s * r2 + 1.0 / 1307674368000.0; s = s * r2 - 1.0 / 6227020800.0;
;     s = s * r2 + 1.0 / 39916800.0; s = s * r2 - 1.0 / 362880.0; s = s * r2 + 1.0 / 5040.0; s = s * r2 - 1.0 / 120.0; s = s * r2 + 1.0 / 6.0;
;     return (float)(r - r * r2 * s);
; __device__ void filter_mlp_phase(unsigned char* smem, int l) {
;     ...
;         { float a = b2[u];
; #pragma unroll 4
;             for (int k = 0; k < 64; ++k) a += ha[ps * 64 + k] * w2[k * 64 + u]; hb[ps * 64 + u] = sin_acc(fr[u] * a, 0.0); }
	v_mov_b32_e32 v25, v231
	ds_read_b128 v[26:29], v21
	ds_read_b128 v[30:33], v21 offset:16
	s_waitcnt lgkmcnt(1)
	v_fmac_f32_e32 v25, v26, v81
	v_fmac_f32_e32 v25, v27, v82
	v_fmac_f32_e32 v25, v28, v83
	v_fmac_f32_e32 v25, v29, v84
	s_waitcnt lgkmcnt(0)
	v_fmac_f32_e32 v25, v30, v85
	v_fmac_f32_e32 v25, v31, v86
	v_fmac_f32_e32 v25, v32, v87
	v_fmac_f32_e32 v25, v33, v88
	ds_read_b128 v[26:29], v21 offset:32
	ds_read_b128 v[30:33], v21 offset:48
	s_waitcnt lgkmcnt(1)
	v_fmac_f32_e32 v25, v26, v89
	v_fmac_f32_e32 v25, v27, v90
	v_fmac_f32_e32 v25, v28, v91
	v_fmac_f32_e32 v25, v29, v92
	s_waitcnt lgkmcnt(0)
	v_fmac_f32_e32 v25, v30, v93
	v_fmac_f32_e32 v25, v31, v94
	v_fmac_f32_e32 v25, v32, v95
	v_fmac_f32_e32 v25, v33, v96
	ds_read_b128 v[26:29], v21 offset:64
	ds_read_b128 v[30:33], v21 offset:80
	s_waitcnt lgkmcnt(1)
	v_fmac_f32_e32 v25, v26, v97
	v_fmac_f32_e32 v25, v27, v98
	v_fmac_f32_e32 v25, v28, v99
	v_fmac_f32_e32 v25, v29, v100
	s_waitcnt lgkmcnt(0)
	v_fmac_f32_e32 v25, v30, v101
	v_fmac_f32_e32 v25, v31, v102
	v_fmac_f32_e32 v25, v32, v103
	v_fmac_f32_e32 v25, v33, v104
	ds_read_b128 v[26:29], v21 offset:96
	ds_read_b128 v[30:33], v21 offset:112
	s_waitcnt lgkmcnt(1)
	v_fmac_f32_e32 v25, v26, v105
	v_fmac_f32_e32 v25, v27, v106
	v_fmac_f32_e32 v25, v28, v107
	v_fmac_f32_e32 v25, v29, v108
	s_waitcnt lgkmcnt(0)
	v_fmac_f32_e32 v25, v30, v109
	v_fmac_f32_e32 v25, v31, v110
	v_fmac_f32_e32 v25, v32, v111
	v_fmac_f32_e32 v25, v33, v112
	ds_read_b128 v[26:29], v21 offset:128
	ds_read_b128 v[30:33], v21 offset:144
	s_waitcnt lgkmcnt(1)
	v_fmac_f32_e32 v25, v26, v113
	v_fmac_f32_e32 v25, v27, v114
	v_fmac_f32_e32 v25, v28, v115
	v_fmac_f32_e32 v25, v29, v116
	s_waitcnt lgkmcnt(0)
	v_fmac_f32_e32 v25, v30, v117
	v_fmac_f32_e32 v25, v31, v118
	v_fmac_f32_e32 v25, v32, v119
	v_fmac_f32_e32 v25, v33, v120
	ds_read_b128 v[26:29], v21 offset:160
	ds_read_b128 v[30:33], v21 offset:176
	s_waitcnt lgkmcnt(1)
	v_fmac_f32_e32 v25, v26, v121
	v_fmac_f32_e32 v25, v27, v122
	v_fmac_f32_e32 v25, v28, v123
	v_fmac_f32_e32 v25, v29, v124
	s_waitcnt lgkmcnt(0)
	v_fmac_f32_e32 v25, v30, v125
	v_fmac_f32_e32 v25, v31, v126
	v_fmac_f32_e32 v25, v32, v127
	v_fmac_f32_e32 v25, v33, v128
	ds_read_b128 v[26:29], v21 offset:192
	ds_read_b128 v[30:33], v21 offset:208
	s_waitcnt lgkmcnt(1)
	v_fmac_f32_e32 v25, v26, v129
	v_fmac_f32_e32 v25, v27, v130
	v_fmac_f32_e32 v25, v28, v131
	v_fmac_f32_e32 v25, v29, v132
	s_waitcnt lgkmcnt(0)
	v_fmac_f32_e32 v25, v30, v133
	v_fmac_f32_e32 v25, v31, v134
	v_fmac_f32_e32 v25, v32, v135
	v_fmac_f32_e32 v25, v33, v136
	ds_read_b128 v[26:29], v21 offset:224
	ds_read_b128 v[30:33], v21 offset:240
	s_waitcnt lgkmcnt(1)
	v_fmac_f32_e32 v25, v26, v137
	v_fmac_f32_e32 v25, v27, v138
	v_fmac_f32_e32 v25, v28, v139
	v_fmac_f32_e32 v25, v29, v142
	s_waitcnt lgkmcnt(0)
	v_fmac_f32_e32 v25, v30, v143
	v_fmac_f32_e32 v25, v31, v144
	v_fmac_f32_e32 v25, v32, v145
	v_fmac_f32_e32 v25, v33, v146
	v_mov_b32_e32 v42, v233
	v_mov_b64_e32 v[14:15], v[188:189]
	v_mov_b64_e32 v[26:27], v[190:191]
	v_mov_b64_e32 v[28:29], v[192:193]
	v_mov_b64_e32 v[30:31], v[194:195]
	v_mov_b64_e32 v[32:33], v[196:197]
	v_mov_b64_e32 v[34:35], v[198:199]
	v_mov_b64_e32 v[36:37], v[200:201]
	v_mov_b64_e32 v[38:39], v[202:203]
	v_mov_b64_e32 v[40:41], v[204:205]
	s_mov_b32 s12, 0
	v_mul_f32_e32 v25, v25, v42
	v_cvt_f64_f32_e32 v[42:43], v25
	v_add_f64 v[42:43], v[42:43], 0
	v_mul_f64 v[44:45], v[42:43], s[22:23]
	v_rndne_f64_e32 v[44:45], v[44:45]
	v_fmac_f64_e32 v[42:43], s[28:29], v[44:45]
	v_mul_f64 v[44:45], v[42:43], v[42:43]
	v_fmac_f64_e32 v[14:15], s[30:31], v[44:45]
	v_fmac_f64_e32 v[26:27], v[44:45], v[14:15]
	v_fmac_f64_e32 v[28:29], v[44:45], v[26:27]
	v_fmac_f64_e32 v[30:31], v[44:45], v[28:29]
	v_fmac_f64_e32 v[32:33], v[44:45], v[30:31]
	v_fmac_f64_e32 v[34:35], v[44:45], v[32:33]
	v_fmac_f64_e32 v[36:37], v[44:45], v[34:35]
	v_fmac_f64_e32 v[38:39], v[44:45], v[36:37]
	v_mul_f64 v[46:47], v[42:43], v[44:45]
	v_fmac_f64_e32 v[40:41], v[44:45], v[38:39]
	v_fma_f64 v[14:15], -v[46:47], v[40:41], v[42:43]
	v_cvt_f32_f64_e32 v14, v[14:15]
	ds_write_b32 v20, v14 offset:3200
	s_waitcnt lgkmcnt(0)
	s_barrier
; __device__ __forceinline__ float sin_acc(float x, double shift) {
;     double xd = (double)x + shift; const double k = rint(xd * 0.15915494309189535); double r = xd - k * 6.283185307179586;
;     const double r2 = r * r; double s = -1.0 / 51090942171709440000.0;
;     s = s * r2 + 1.0 / 121645100408832000.0; s = s * r2 - 1.0 / 355687428096000.0; s = s * r2 + 1.0 / 1307674368000.0; s = s * r2 - 1.0 / 6227020800.0;
;     s = s * r2 + 1.0 / 39916800.0; s = s * r2 - 1.0 / 362880.0; s = s * r2 + 1.0 / 5040.0; s = s * r2 - 1.0 / 120.0; s = s * r2 + 1.0 / 6.0;
;     return (float)(r - r * r2 * s);
; __device__ void filter_mlp_phase(unsigned char* smem, int l) {
;     ...
;         { float a = b3[u];
; #pragma unroll 4
;             for (int k = 0; k < 64; ++k) a += hb[ps * 64 + k] * w3[k * 64 + u]; hdn[pos * 64 + u] = sin_acc(fr[u] * a, 0.0); }
	s_waitcnt vmcnt(0)
	v_mov_b32_e32 v25, v232
	ds_read_b128 v[26:29], v22
	ds_read_b128 v[30:33], v22 offset:16
	s_waitcnt lgkmcnt(1)
	v_fmac_f32_e32 v25, v26, v48
	v_fmac_f32_e32 v25, v27, v49
	v_fmac_f32_e32 v25, v28, v50
	v_fmac_f32_e32 v25, v29, v51
	s_waitcnt lgkmcnt(0)
	v_fmac_f32_e32 v25, v30, v52
	v_fmac_f32_e32 v25, v31, v53
	v_fmac_f32_e32 v25, v32, v54
	v_fmac_f32_e32 v25, v33, v55
	ds_read_b128 v[26:29], v22 offset:32
	ds_read_b128 v[30:33], v22 offset:48
	s_waitcnt lgkmcnt(1)
	v_fmac_f32_e32 v25, v26, v56
	v_fmac_f32_e32 v25, v27, v57
	v_fmac_f32_e32 v25, v28, v58
	v_fmac_f32_e32 v25, v29, v59
	s_waitcnt lgkmcnt(0)
	v_fmac_f32_e32 v25, v30, v60
	v_fmac_f32_e32 v25, v31, v61
	v_fmac_f32_e32 v25, v32, v62
	v_fmac_f32_e32 v25, v33, v63
	ds_read_b128 v[26:29], v22 offset:64
	ds_read_b128 v[30:33], v22 offset:80
	s_waitcnt lgkmcnt(1)
	v_fmac_f32_e32 v25, v26, v64
	v_fmac_f32_e32 v25, v27, v65
	v_fmac_f32_e32 v25, v28, v66
	v_fmac_f32_e32 v25, v29, v67
	s_waitcnt lgkmcnt(0)
	v_fmac_f32_e32 v25, v30, v68
	v_fmac_f32_e32 v25, v31, v69
	v_fmac_f32_e32 v25, v32, v70
	v_fmac_f32_e32 v25, v33, v71
	ds_read_b128 v[26:29], v22 offset:96
	ds_read_b128 v[30:33], v22 offset:112
	s_waitcnt lgkmcnt(1)
	v_fmac_f32_e32 v25, v26, v72
	v_fmac_f32_e32 v25, v27, v73
	v_fmac_f32_e32 v25, v28, v74
	v_fmac_f32_e32 v25, v29, v75
	s_waitcnt lgkmcnt(0)
	v_fmac_f32_e32 v25, v30, v76
	v_fmac_f32_e32 v25, v31, v77
	v_fmac_f32_e32 v25, v32, v78
	v_fmac_f32_e32 v25, v33, v79
	ds_read_b128 v[26:29], v22 offset:128
	ds_read_b128 v[30:33], v22 offset:144
	s_waitcnt lgkmcnt(1)
	v_fmac_f32_e32 v25, v26, v80
	v_fmac_f32_e32 v25, v27, v147
	v_fmac_f32_e32 v25, v28, v148
	v_fmac_f32_e32 v25, v29, v149
	s_waitcnt lgkmcnt(0)
	v_fmac_f32_e32 v25, v30, v150
	v_fmac_f32_e32 v25, v31, v151
	v_fmac_f32_e32 v25, v32, v152
	v_fmac_f32_e32 v25, v33, v153
	ds_read_b128 v[26:29], v22 offset:160
	ds_read_b128 v[30:33], v22 offset:176
	s_waitcnt lgkmcnt(1)
	v_fmac_f32_e32 v25, v26, v154
	v_fmac_f32_e32 v25, v27, v155
	v_fmac_f32_e32 v25, v28, v156
	v_fmac_f32_e32 v25, v29, v157
	s_waitcnt lgkmcnt(0)
	v_fmac_f32_e32 v25, v30, v158
	v_fmac_f32_e32 v25, v31, v159
	v_fmac_f32_e32 v25, v32, v160
	v_fmac_f32_e32 v25, v33, v161
	ds_read_b128 v[26:29], v22 offset:192
	ds_read_b128 v[30:33], v22 offset:208
	s_waitcnt lgkmcnt(1)
	v_fmac_f32_e32 v25, v26, v162
	v_fmac_f32_e32 v25, v27, v163
	v_fmac_f32_e32 v25, v28, v164
	v_fmac_f32_e32 v25, v29, v165
	s_waitcnt lgkmcnt(0)
	v_fmac_f32_e32 v25, v30, v166
	v_fmac_f32_e32 v25, v31, v167
	v_fmac_f32_e32 v25, v32, v168
	v_fmac_f32_e32 v25, v33, v169
	ds_read_b128 v[26:29], v22 offset:224
	ds_read_b128 v[30:33], v22 offset:240
	s_waitcnt lgkmcnt(1)
	v_fmac_f32_e32 v25, v26, v170
	v_fmac_f32_e32 v25, v27, v171
	v_fmac_f32_e32 v25, v28, v172
	v_fmac_f32_e32 v25, v29, v173
	s_waitcnt lgkmcnt(0)
	v_fmac_f32_e32 v25, v30, v174
	v_fmac_f32_e32 v25, v31, v175
	v_fmac_f32_e32 v25, v32, v176
	v_fmac_f32_e32 v25, v33, v177
	v_mov_b32_e32 v44, v233
	v_lshl_or_b32 v42, v24, 6, v16
	v_mov_b64_e32 v[14:15], v[188:189]
	v_mov_b64_e32 v[26:27], v[190:191]
	v_mov_b64_e32 v[28:29], v[192:193]
	v_mov_b64_e32 v[30:31], v[194:195]
	v_mov_b64_e32 v[32:33], v[196:197]
	v_mov_b64_e32 v[34:35], v[198:199]
	v_mov_b64_e32 v[36:37], v[200:201]
	v_mov_b64_e32 v[38:39], v[202:203]
	v_mov_b64_e32 v[40:41], v[204:205]
	s_add_i32 s14, s14, s5
	v_ashrrev_i32_e32 v43, 31, v42
	v_lshl_add_u64 v[42:43], v[42:43], 2, s[6:7]
	s_cmpk_gt_i32 s14, 0xff
	s_waitcnt vmcnt(0)
	v_mul_f32_e32 v24, v25, v44
	v_cvt_f64_f32_e32 v[24:25], v24
	v_add_f64 v[24:25], v[24:25], 0
	v_mul_f64 v[44:45], v[24:25], s[22:23]
	v_rndne_f64_e32 v[44:45], v[44:45]
	v_fmac_f64_e32 v[24:25], s[28:29], v[44:45]
	v_mul_f64 v[44:45], v[24:25], v[24:25]
	v_fmac_f64_e32 v[14:15], s[30:31], v[44:45]
	v_fmac_f64_e32 v[26:27], v[44:45], v[14:15]
	v_fmac_f64_e32 v[28:29], v[44:45], v[26:27]
	v_fmac_f64_e32 v[30:31], v[44:45], v[28:29]
	v_fmac_f64_e32 v[32:33], v[44:45], v[30:31]
	v_fmac_f64_e32 v[34:35], v[44:45], v[32:33]
	v_fmac_f64_e32 v[36:37], v[44:45], v[34:35]
	v_fmac_f64_e32 v[38:39], v[44:45], v[36:37]
	v_mul_f64 v[46:47], v[24:25], v[44:45]
	v_fmac_f64_e32 v[40:41], v[44:45], v[38:39]
	v_fma_f64 v[14:15], -v[46:47], v[40:41], v[24:25]
	v_cvt_f32_f64_e32 v14, v[14:15]
	global_store_dword v[42:43], v14, off
	s_cbranch_scc0 .LBB0_383
